# P2b attention: key tiles that need no causal mask for the wave run a copy of the step body without the per-element index/compare/select chain
# speedup vs baseline: 1.0265x; 1.0060x over previous
.LBB0_400:
	s_add_i32 s0, s6, 64
	v_cmp_le_i32_e32 vcc, s0, v130
	s_and_saveexec_b64 s[12:13], vcc
	s_cbranch_execz .LBB0_402
	v_add_u32_e32 v0, v131, v122
	ds_read_b128 v[138:141], v0 offset:13824
	ds_read_b128 v[50:53], v0 offset:9216
	ds_read_b128 v[142:145], v0 offset:9248
	s_add_i32 s0, s6, 0x7f
	v_cmp_gt_i32_e32 vcc, s0, v128
	s_waitcnt lgkmcnt(1)
	v_mfma_f32_32x32x16_bf16 v[66:81], v[50:53], v[82:85], v[34:49]
	v_mfma_f32_32x32x16_bf16 v[50:65], v[138:141], v[82:85], v[34:49]
	ds_read_b128 v[138:141], v0 offset:13856
	s_waitcnt lgkmcnt(1)
	v_mfma_f32_32x32x16_bf16 v[66:81], v[142:145], v[86:89], v[66:81]
	s_waitcnt lgkmcnt(0)
	v_mfma_f32_32x32x16_bf16 v[50:65], v[138:141], v[86:89], v[50:65]
	ds_read_b128 v[138:141], v0 offset:9280
	ds_read_b128 v[142:145], v0 offset:13888
	s_waitcnt lgkmcnt(1)
	v_mfma_f32_32x32x16_bf16 v[66:81], v[138:141], v[90:93], v[66:81]
	s_waitcnt lgkmcnt(0)
	v_mfma_f32_32x32x16_bf16 v[50:65], v[142:145], v[90:93], v[50:65]
	ds_read_b128 v[138:141], v0 offset:9312
	ds_read_b128 v[142:145], v0 offset:13920
	v_add_u32_e32 v0, s6, v118
	v_add_u32_e32 v137, 64, v0
	v_cmp_gt_i32_e64 s[0:1], v137, v120
	s_cbranch_vccz .Lattn_fast_B
	s_and_b64 s[0:1], vcc, s[0:1]
	v_add_u32_e32 v148, 0x50, v0
	s_waitcnt lgkmcnt(1)
	v_mfma_f32_32x32x16_bf16 v[66:81], v[138:141], v[94:97], v[66:81]
	s_waitcnt lgkmcnt(0)
	v_mfma_f32_32x32x16_bf16 v[50:65], v[142:145], v[94:97], v[50:65]
	ds_read_b128 v[138:141], v134 offset:37120
	ds_read_b128 v[142:145], v134 offset:37136
	s_waitcnt lgkmcnt(1)
	s_nop 6
	v_add_f32_e32 v66, v66, v138
	v_cndmask_b32_e64 v138, v66, v210, s[0:1]
	v_cmp_ge_i32_e64 s[0:1], v137, v120
	v_add_f32_e32 v66, v67, v139
	s_and_b64 s[0:1], vcc, s[0:1]
	v_cndmask_b32_e64 v137, v66, v210, s[0:1]
	s_mov_b32 s0, 0xf149f2ca
	v_add_f32_e32 v67, v68, v140
	v_add_u32_e32 v68, 0x42, v0
	v_max3_f32 v66, v138, s0, v137
	v_cmp_gt_i32_e64 s[0:1], v68, v120
	s_and_b64 s[0:1], vcc, s[0:1]
	v_add_u32_e32 v68, 0x43, v0
	v_cndmask_b32_e64 v139, v67, v210, s[0:1]
	v_cmp_gt_i32_e64 s[0:1], v68, v120
	v_add_f32_e32 v67, v69, v141
	s_and_b64 s[0:1], vcc, s[0:1]
	v_add_u32_e32 v68, 0x44, v0
	v_cndmask_b32_e64 v140, v67, v210, s[0:1]
	v_cmp_gt_i32_e64 s[0:1], v68, v120
	s_waitcnt lgkmcnt(0)
	v_add_f32_e32 v67, v70, v142
	s_and_b64 s[0:1], vcc, s[0:1]
	v_add_u32_e32 v68, 0x45, v0
	v_cndmask_b32_e64 v141, v67, v210, s[0:1]
	v_cmp_gt_i32_e64 s[0:1], v68, v120
	v_add_f32_e32 v67, v71, v143
	s_and_b64 s[0:1], vcc, s[0:1]
	v_add_u32_e32 v68, 0x46, v0
	v_cndmask_b32_e64 v142, v67, v210, s[0:1]
	v_cmp_gt_i32_e64 s[0:1], v68, v120
	v_add_f32_e32 v67, v72, v144
	s_and_b64 s[0:1], vcc, s[0:1]
	v_add_u32_e32 v68, 0x47, v0
	v_cndmask_b32_e64 v143, v67, v210, s[0:1]
	v_cmp_gt_i32_e64 s[0:1], v68, v120
	v_max3_f32 v66, v66, v139, v140
	v_add_f32_e32 v67, v73, v145
	s_and_b64 s[0:1], vcc, s[0:1]
	v_max3_f32 v66, v66, v141, v142
	v_cndmask_b32_e64 v144, v67, v210, s[0:1]
	v_max3_f32 v145, v66, v143, v144
	ds_read_b128 v[66:69], v134 offset:37184
	ds_read_b128 v[70:73], v134 offset:37200
	v_cmp_gt_i32_e64 s[0:1], v148, v120
	s_and_b64 s[0:1], vcc, s[0:1]
	s_waitcnt lgkmcnt(1)
	v_add_f32_e32 v66, v74, v66
	v_cndmask_b32_e64 v74, v66, v210, s[0:1]
	v_cmp_ge_i32_e64 s[0:1], v148, v120
	v_add_f32_e32 v66, v75, v67
	s_and_b64 s[0:1], vcc, s[0:1]
	v_add_f32_e32 v67, v76, v68
	v_add_u32_e32 v68, 0x52, v0
	v_cndmask_b32_e64 v75, v66, v210, s[0:1]
	v_cmp_gt_i32_e64 s[0:1], v68, v120
	s_and_b64 s[0:1], vcc, s[0:1]
	v_add_u32_e32 v68, 0x53, v0
	v_cndmask_b32_e64 v76, v67, v210, s[0:1]
	v_cmp_gt_i32_e64 s[0:1], v68, v120
	v_add_f32_e32 v67, v77, v69
	s_and_b64 s[0:1], vcc, s[0:1]
	v_add_u32_e32 v68, 0x54, v0
	v_cndmask_b32_e64 v77, v67, v210, s[0:1]
	v_cmp_gt_i32_e64 s[0:1], v68, v120
	s_waitcnt lgkmcnt(0)
	v_add_f32_e32 v67, v78, v70
	s_and_b64 s[0:1], vcc, s[0:1]
	v_add_u32_e32 v68, 0x55, v0
	v_cndmask_b32_e64 v78, v67, v210, s[0:1]
	v_cmp_gt_i32_e64 s[0:1], v68, v120
	v_add_f32_e32 v67, v79, v71
	s_and_b64 s[0:1], vcc, s[0:1]
	v_add_u32_e32 v68, 0x56, v0
	v_max3_f32 v66, v145, v74, v75
	v_cndmask_b32_e64 v145, v67, v210, s[0:1]
	v_cmp_gt_i32_e64 s[0:1], v68, v120
	v_add_f32_e32 v67, v80, v72
	s_and_b64 s[0:1], vcc, s[0:1]
	v_add_u32_e32 v68, 0x57, v0
	v_cndmask_b32_e64 v148, v67, v210, s[0:1]
	v_cmp_gt_i32_e64 s[0:1], v68, v120
	v_max3_f32 v66, v66, v76, v77
	v_add_f32_e32 v67, v81, v73
	s_and_b64 s[0:1], vcc, s[0:1]
	v_max3_f32 v66, v66, v78, v145
	v_cndmask_b32_e64 v81, v67, v210, s[0:1]
	v_max3_f32 v79, v66, v148, v81
	ds_read_b128 v[66:69], v134 offset:37248
	ds_read_b128 v[70:73], v134 offset:37264
	v_add_u32_e32 v80, 0x60, v0
	v_cmp_gt_i32_e64 s[0:1], v80, v120
	s_and_b64 s[0:1], vcc, s[0:1]
	s_waitcnt lgkmcnt(1)
	v_add_f32_e32 v50, v50, v66
	v_cndmask_b32_e64 v66, v50, v210, s[0:1]
	v_cmp_ge_i32_e64 s[0:1], v80, v120
	v_add_f32_e32 v50, v51, v67
	s_and_b64 s[0:1], vcc, s[0:1]
	v_add_f32_e32 v51, v52, v68
	v_add_u32_e32 v52, 0x62, v0
	v_cndmask_b32_e64 v67, v50, v210, s[0:1]
	v_cmp_gt_i32_e64 s[0:1], v52, v120
	s_and_b64 s[0:1], vcc, s[0:1]
	v_add_u32_e32 v52, 0x63, v0
	v_cndmask_b32_e64 v68, v51, v210, s[0:1]
	v_cmp_gt_i32_e64 s[0:1], v52, v120
	v_add_f32_e32 v51, v53, v69
	s_and_b64 s[0:1], vcc, s[0:1]
	v_add_u32_e32 v52, 0x64, v0
	v_cndmask_b32_e64 v69, v51, v210, s[0:1]
	v_cmp_gt_i32_e64 s[0:1], v52, v120
	s_waitcnt lgkmcnt(0)
	v_add_f32_e32 v51, v54, v70
	s_and_b64 s[0:1], vcc, s[0:1]
	v_add_u32_e32 v52, 0x65, v0
	v_cndmask_b32_e64 v70, v51, v210, s[0:1]
	v_cmp_gt_i32_e64 s[0:1], v52, v120
	v_add_f32_e32 v51, v55, v71
	s_and_b64 s[0:1], vcc, s[0:1]
	v_add_u32_e32 v52, 0x66, v0
	v_cndmask_b32_e64 v71, v51, v210, s[0:1]
	v_cmp_gt_i32_e64 s[0:1], v52, v120
	v_add_f32_e32 v51, v56, v72
	s_and_b64 s[0:1], vcc, s[0:1]
	v_add_u32_e32 v52, 0x67, v0
	v_max3_f32 v50, v79, v66, v67
	v_cndmask_b32_e64 v72, v51, v210, s[0:1]
	v_cmp_gt_i32_e64 s[0:1], v52, v120
	v_max3_f32 v50, v50, v68, v69
	v_add_f32_e32 v51, v57, v73
	s_and_b64 s[0:1], vcc, s[0:1]
	v_max3_f32 v50, v50, v70, v71
	v_cndmask_b32_e64 v73, v51, v210, s[0:1]
	v_max3_f32 v79, v50, v72, v73
	ds_read_b128 v[50:53], v134 offset:37312
	ds_read_b128 v[54:57], v134 offset:37328
	v_add_u32_e32 v80, 0x70, v0
	v_cmp_gt_i32_e64 s[0:1], v80, v120
	s_and_b64 s[0:1], vcc, s[0:1]
	s_waitcnt lgkmcnt(1)
	v_add_f32_e32 v50, v58, v50
	v_cndmask_b32_e64 v149, v50, v210, s[0:1]
	v_cmp_ge_i32_e64 s[0:1], v80, v120
	v_add_f32_e32 v50, v59, v51
	s_and_b64 s[0:1], vcc, s[0:1]
	v_add_f32_e32 v51, v60, v52
	v_add_u32_e32 v52, 0x72, v0
	v_cndmask_b32_e64 v80, v50, v210, s[0:1]
	v_cmp_gt_i32_e64 s[0:1], v52, v120
	s_and_b64 s[0:1], vcc, s[0:1]
	v_add_u32_e32 v52, 0x73, v0
	v_max3_f32 v50, v79, v149, v80
	v_cndmask_b32_e64 v79, v51, v210, s[0:1]
	v_cmp_gt_i32_e64 s[0:1], v52, v120
	v_add_f32_e32 v51, v61, v53
	s_and_b64 s[0:1], vcc, s[0:1]
	v_add_u32_e32 v52, 0x74, v0
	v_cndmask_b32_e64 v53, v51, v210, s[0:1]
	v_cmp_gt_i32_e64 s[0:1], v52, v120
	s_waitcnt lgkmcnt(0)
	v_add_f32_e32 v51, v62, v54
	s_and_b64 s[0:1], vcc, s[0:1]
	v_add_u32_e32 v52, 0x75, v0
	v_cndmask_b32_e64 v62, v51, v210, s[0:1]
	v_cmp_gt_i32_e64 s[0:1], v52, v120
	v_add_f32_e32 v51, v63, v55
	s_and_b64 s[0:1], vcc, s[0:1]
	v_add_u32_e32 v52, 0x76, v0
	v_cndmask_b32_e64 v162, v51, v210, s[0:1]
	v_cmp_gt_i32_e64 s[0:1], v52, v120
	v_add_f32_e32 v51, v64, v56
	s_and_b64 s[0:1], vcc, s[0:1]
	v_add_u32_e32 v0, 0x77, v0
	v_cndmask_b32_e64 v163, v51, v210, s[0:1]
	v_cmp_gt_i32_e64 s[0:1], v0, v120
	v_max3_f32 v50, v50, v79, v53
	v_add_f32_e32 v51, v65, v57
	s_and_b64 vcc, vcc, s[0:1]
	v_max3_f32 v50, v50, v62, v162
	v_cndmask_b32_e32 v57, v51, v210, vcc
	v_and_b32_e32 v51, 64, v207
	v_max3_f32 v0, v50, v163, v57
	v_xor_b32_e32 v50, 32, v207
	v_add_u32_e32 v51, 64, v51
	v_cmp_lt_i32_e32 vcc, v50, v51
	s_nop 1
	v_cndmask_b32_e32 v50, v207, v50, vcc
	v_lshlrev_b32_e32 v50, 2, v50
	ds_bpermute_b32 v50, v50, v0
	s_waitcnt lgkmcnt(0)
	v_max3_f32 v63, v136, v0, v50
	v_sub_f32_e32 v0, v138, v63
	v_exp_f32_e32 v164, v0
	v_sub_f32_e32 v0, v66, v63
	v_sub_f32_e32 v52, v139, v63
	v_exp_f32_e32 v165, v0
	v_sub_f32_e32 v0, v137, v63
	v_exp_f32_e32 v166, v52
	v_sub_f32_e32 v52, v68, v63
	v_sub_f32_e32 v56, v141, v63
	v_sub_f32_e32 v53, v53, v63
	v_exp_f32_e32 v50, v0
	v_sub_f32_e32 v0, v67, v63
	v_exp_f32_e32 v167, v52
	v_sub_f32_e32 v52, v140, v63
	v_exp_f32_e32 v140, v56
	v_sub_f32_e32 v56, v70, v63
	v_sub_f32_e32 v60, v143, v63
	v_sub_f32_e32 v67, v76, v63
	v_exp_f32_e32 v76, v53
	v_sub_f32_e32 v53, v78, v63
	v_exp_f32_e32 v141, v56
	v_sub_f32_e32 v56, v142, v63
	v_exp_f32_e32 v142, v60
	v_sub_f32_e32 v60, v72, v63
	v_sub_f32_e32 v66, v74, v63
	v_exp_f32_e32 v170, v53
	v_sub_f32_e32 v53, v62, v63
	v_exp_f32_e32 v0, v0
	v_exp_f32_e32 v143, v60
	v_sub_f32_e32 v60, v144, v63
	v_exp_f32_e32 v144, v66
	v_sub_f32_e32 v66, v149, v63
	v_exp_f32_e32 v171, v53
	v_sub_f32_e32 v53, v145, v63
	v_exp_f32_e32 v149, v66
	v_sub_f32_e32 v66, v75, v63
	v_exp_f32_e32 v78, v53
	v_sub_f32_e32 v53, v162, v63
	v_exp_f32_e32 v54, v52
	v_sub_f32_e32 v52, v69, v63
	v_exp_f32_e32 v68, v66
	v_sub_f32_e32 v66, v80, v63
	v_exp_f32_e32 v80, v53
	v_sub_f32_e32 v53, v148, v63
	v_add_f32_e32 v51, v164, v165
	v_exp_f32_e32 v52, v52
	v_exp_f32_e32 v145, v53
	v_sub_f32_e32 v53, v163, v63
	v_exp_f32_e32 v58, v56
	v_sub_f32_e32 v56, v71, v63
	v_exp_f32_e32 v148, v53
	v_sub_f32_e32 v53, v81, v63
	v_pk_add_f32 v[70:71], v[50:51], v[0:1]
	v_sub_f32_e32 v65, v136, v63
	v_exp_f32_e32 v136, v53
	v_sub_f32_e32 v53, v57, v63
	v_pk_add_f32 v[70:71], v[70:71], v[70:71] op_sel_hi:[0,1]
	v_add_f32_e32 v55, v166, v167
	v_exp_f32_e32 v56, v56
	v_exp_f32_e32 v138, v53
	v_mov_b32_e32 v53, v71
	v_pk_add_f32 v[70:71], v[54:55], v[52:53]
	v_sub_f32_e32 v64, v73, v63
	v_pk_add_f32 v[70:71], v[70:71], v[70:71] op_sel_hi:[0,1]
	v_add_f32_e32 v59, v140, v141
	v_exp_f32_e32 v60, v60
	v_exp_f32_e32 v64, v64
	v_mov_b32_e32 v57, v71
	v_pk_add_f32 v[70:71], v[58:59], v[56:57]
	v_add_f32_e32 v61, v142, v143
	v_pk_add_f32 v[70:71], v[70:71], v[70:71] op_sel_hi:[0,1]
	v_exp_f32_e32 v66, v66
	v_exp_f32_e32 v62, v65
	v_mov_b32_e32 v65, v71
	v_exp_f32_e32 v168, v67
	v_sub_f32_e32 v67, v79, v63
	v_pk_add_f32 v[70:71], v[60:61], v[64:65]
	v_exp_f32_e32 v169, v67
	v_sub_f32_e32 v67, v77, v63
	v_pk_add_f32 v[70:71], v[70:71], v[70:71] op_sel_hi:[0,1]
	v_add_f32_e32 v69, v144, v149
	v_exp_f32_e32 v74, v67
	v_mov_b32_e32 v67, v71
	v_pk_add_f32 v[70:71], v[68:69], v[66:67]
	v_add_f32_e32 v75, v168, v169
	v_pk_add_f32 v[70:71], v[70:71], v[70:71] op_sel_hi:[0,1]
	v_mov_b32_e32 v77, v71
	v_pk_add_f32 v[70:71], v[74:75], v[76:77]
	v_add_f32_e32 v79, v170, v171
	v_pk_add_f32 v[70:71], v[70:71], v[70:71] op_sel_hi:[0,1]
	v_mov_b32_e32 v81, v71
	v_pk_add_f32 v[70:71], v[78:79], v[80:81]
	v_add_f32_e32 v137, v145, v148
	v_pk_add_f32 v[70:71], v[70:71], v[70:71] op_sel_hi:[0,1]
	v_mov_b32_e32 v139, v71
	v_pk_add_f32 v[70:71], v[136:137], v[138:139]
	v_cvt_pk_bf16_f32 v72, v140, v58
	v_add_f32_e32 v65, v70, v71
	v_cvt_pk_bf16_f32 v71, v166, v54
	v_cvt_pk_bf16_f32 v54, v165, v0
	v_add_u32_e32 v0, v132, v122
	v_cvt_pk_bf16_f32 v70, v164, v50
	v_cvt_pk_bf16_f32 v73, v142, v60
	v_cvt_pk_bf16_f32 v58, v144, v68
	v_cvt_pk_bf16_f32 v59, v168, v74
	v_cvt_pk_bf16_f32 v60, v170, v78
	v_cvt_pk_bf16_f32 v55, v167, v52
	v_cvt_pk_bf16_f32 v50, v149, v66
	v_cvt_pk_bf16_f32 v51, v169, v76
	v_cvt_pk_bf16_f32 v52, v171, v80
	ds_read_b128 v[66:69], v0 offset:32256
	ds_read_b128 v[74:77], v0 offset:27648
	ds_read_b128 v[78:81], v0 offset:27680
	v_pk_mul_f32 v[16:17], v[16:17], v[62:63] op_sel_hi:[1,0]
	v_pk_mul_f32 v[14:15], v[14:15], v[62:63] op_sel_hi:[1,0]
	v_pk_mul_f32 v[12:13], v[12:13], v[62:63] op_sel_hi:[1,0]
	v_pk_mul_f32 v[10:11], v[10:11], v[62:63] op_sel_hi:[1,0]
	v_pk_mul_f32 v[8:9], v[8:9], v[62:63] op_sel_hi:[1,0]
	v_pk_mul_f32 v[6:7], v[6:7], v[62:63] op_sel_hi:[1,0]
	v_pk_mul_f32 v[4:5], v[4:5], v[62:63] op_sel_hi:[1,0]
	v_pk_mul_f32 v[2:3], v[2:3], v[62:63] op_sel_hi:[1,0]
	v_pk_mul_f32 v[32:33], v[32:33], v[62:63] op_sel_hi:[1,0]
	v_pk_mul_f32 v[30:31], v[30:31], v[62:63] op_sel_hi:[1,0]
	v_pk_mul_f32 v[28:29], v[28:29], v[62:63] op_sel_hi:[1,0]
	v_pk_mul_f32 v[26:27], v[26:27], v[62:63] op_sel_hi:[1,0]
	v_pk_mul_f32 v[24:25], v[24:25], v[62:63] op_sel_hi:[1,0]
	v_pk_mul_f32 v[22:23], v[22:23], v[62:63] op_sel_hi:[1,0]
	v_pk_mul_f32 v[20:21], v[20:21], v[62:63] op_sel_hi:[1,0]
	v_pk_mul_f32 v[18:19], v[18:19], v[62:63] op_sel_hi:[1,0]
	s_waitcnt lgkmcnt(2)
	v_mfma_f32_32x32x16_bf16 v[2:17], v[66:69], v[70:73], v[2:17]
	ds_read_b128 v[66:69], v0 offset:32288
	v_cvt_pk_bf16_f32 v61, v145, v136
	v_cvt_pk_bf16_f32 v56, v141, v56
	v_cvt_pk_bf16_f32 v57, v143, v64
	v_cvt_pk_bf16_f32 v53, v148, v138
	v_fmac_f32_e32 v65, v133, v62
	v_mov_b32_e32 v136, v63
	s_waitcnt lgkmcnt(2)
	v_mfma_f32_32x32x16_bf16 v[18:33], v[74:77], v[70:73], v[18:33]
	v_mov_b32_e32 v133, v65
	s_waitcnt lgkmcnt(1)
	v_mfma_f32_32x32x16_bf16 v[18:33], v[78:81], v[58:61], v[18:33]
	s_waitcnt lgkmcnt(0)
	v_mfma_f32_32x32x16_bf16 v[2:17], v[66:69], v[58:61], v[2:17]
	ds_read_b128 v[58:61], v0 offset:27712
	ds_read_b128 v[66:69], v0 offset:32320
	s_waitcnt lgkmcnt(1)
	v_mfma_f32_32x32x16_bf16 v[18:33], v[58:61], v[54:57], v[18:33]
	s_waitcnt lgkmcnt(0)
	v_mfma_f32_32x32x16_bf16 v[2:17], v[66:69], v[54:57], v[2:17]
	ds_read_b128 v[54:57], v0 offset:27744
	ds_read_b128 v[58:61], v0 offset:32352
	s_waitcnt lgkmcnt(1)
	v_mfma_f32_32x32x16_bf16 v[18:33], v[54:57], v[50:53], v[18:33]
	s_waitcnt lgkmcnt(0)
	v_mfma_f32_32x32x16_bf16 v[2:17], v[58:61], v[50:53], v[2:17]

.LBB0_404:
	v_add_u32_e32 v0, v131, v122
	ds_read_b128 v[138:141], v0 offset:4608
	ds_read_b128 v[50:53], v0
	ds_read_b128 v[142:145], v0 offset:32
	s_add_i32 s0, s6, 63
	v_cmp_gt_i32_e32 vcc, s0, v128
	s_waitcnt lgkmcnt(1)
	v_mfma_f32_32x32x16_bf16 v[66:81], v[50:53], v[82:85], v[34:49]
	v_mfma_f32_32x32x16_bf16 v[50:65], v[138:141], v[82:85], v[34:49]
	ds_read_b128 v[138:141], v0 offset:4640
	s_waitcnt lgkmcnt(1)
	v_mfma_f32_32x32x16_bf16 v[66:81], v[142:145], v[86:89], v[66:81]
	s_waitcnt lgkmcnt(0)
	v_mfma_f32_32x32x16_bf16 v[50:65], v[138:141], v[86:89], v[50:65]
	ds_read_b128 v[138:141], v0 offset:64
	ds_read_b128 v[142:145], v0 offset:4672
	s_waitcnt lgkmcnt(1)
	v_mfma_f32_32x32x16_bf16 v[66:81], v[138:141], v[90:93], v[66:81]
	s_waitcnt lgkmcnt(0)
	v_mfma_f32_32x32x16_bf16 v[50:65], v[142:145], v[90:93], v[50:65]
	ds_read_b128 v[138:141], v0 offset:96
	ds_read_b128 v[142:145], v0 offset:4704
	v_add_u32_e32 v0, s6, v118
	v_cmp_gt_i32_e64 s[0:1], v0, v120
	s_and_b64 s[0:1], vcc, s[0:1]
	s_cbranch_vccz .Lattn_fast_A
	v_add_u32_e32 v148, 16, v0
	s_waitcnt lgkmcnt(1)
	v_mfma_f32_32x32x16_bf16 v[66:81], v[138:141], v[94:97], v[66:81]
	s_waitcnt lgkmcnt(0)
	v_mfma_f32_32x32x16_bf16 v[50:65], v[142:145], v[94:97], v[50:65]
	ds_read_b128 v[138:141], v134 offset:36864
	ds_read_b128 v[142:145], v134 offset:36880
	s_waitcnt lgkmcnt(1)
	s_nop 6
	v_add_f32_e32 v66, v66, v138
	v_cndmask_b32_e64 v137, v66, v210, s[0:1]
	v_cmp_ge_i32_e64 s[0:1], v0, v120
	v_add_f32_e32 v66, v67, v139
	s_and_b64 s[0:1], vcc, s[0:1]
	v_cndmask_b32_e64 v138, v66, v210, s[0:1]
	s_mov_b32 s0, 0xf149f2ca
	v_add_f32_e32 v67, v68, v140
	v_add_u32_e32 v68, 2, v0
	v_max3_f32 v66, v137, s0, v138
	v_cmp_gt_i32_e64 s[0:1], v68, v120
	s_and_b64 s[0:1], vcc, s[0:1]
	v_add_u32_e32 v68, 3, v0
	v_cndmask_b32_e64 v139, v67, v210, s[0:1]
	v_cmp_gt_i32_e64 s[0:1], v68, v120
	v_add_f32_e32 v67, v69, v141
	s_and_b64 s[0:1], vcc, s[0:1]
	v_add_u32_e32 v68, 4, v0
	v_cndmask_b32_e64 v140, v67, v210, s[0:1]
	v_cmp_gt_i32_e64 s[0:1], v68, v120
	s_waitcnt lgkmcnt(0)
	v_add_f32_e32 v67, v70, v142
	s_and_b64 s[0:1], vcc, s[0:1]
	v_add_u32_e32 v68, 5, v0
	v_cndmask_b32_e64 v141, v67, v210, s[0:1]
	v_cmp_gt_i32_e64 s[0:1], v68, v120
	v_add_f32_e32 v67, v71, v143
	s_and_b64 s[0:1], vcc, s[0:1]
	v_add_u32_e32 v68, 6, v0
	v_cndmask_b32_e64 v142, v67, v210, s[0:1]
	v_cmp_gt_i32_e64 s[0:1], v68, v120
	v_add_f32_e32 v67, v72, v144
	s_and_b64 s[0:1], vcc, s[0:1]
	v_add_u32_e32 v68, 7, v0
	v_cndmask_b32_e64 v143, v67, v210, s[0:1]
	v_cmp_gt_i32_e64 s[0:1], v68, v120
	v_max3_f32 v66, v66, v139, v140
	v_add_f32_e32 v67, v73, v145
	s_and_b64 s[0:1], vcc, s[0:1]
	v_max3_f32 v66, v66, v141, v142
	v_cndmask_b32_e64 v144, v67, v210, s[0:1]
	v_max3_f32 v145, v66, v143, v144
	ds_read_b128 v[66:69], v134 offset:36928
	ds_read_b128 v[70:73], v134 offset:36944
	v_cmp_gt_i32_e64 s[0:1], v148, v120
	s_and_b64 s[0:1], vcc, s[0:1]
	s_waitcnt lgkmcnt(1)
	v_add_f32_e32 v66, v74, v66
	v_cndmask_b32_e64 v74, v66, v210, s[0:1]
	v_cmp_ge_i32_e64 s[0:1], v148, v120
	v_add_f32_e32 v66, v75, v67
	s_and_b64 s[0:1], vcc, s[0:1]
	v_add_f32_e32 v67, v76, v68
	v_add_u32_e32 v68, 18, v0
	v_cndmask_b32_e64 v75, v66, v210, s[0:1]
	v_cmp_gt_i32_e64 s[0:1], v68, v120
	s_and_b64 s[0:1], vcc, s[0:1]
	v_add_u32_e32 v68, 19, v0
	v_cndmask_b32_e64 v76, v67, v210, s[0:1]
	v_cmp_gt_i32_e64 s[0:1], v68, v120
	v_add_f32_e32 v67, v77, v69
	s_and_b64 s[0:1], vcc, s[0:1]
	v_add_u32_e32 v68, 20, v0
	v_cndmask_b32_e64 v77, v67, v210, s[0:1]
	v_cmp_gt_i32_e64 s[0:1], v68, v120
	s_waitcnt lgkmcnt(0)
	v_add_f32_e32 v67, v78, v70
	s_and_b64 s[0:1], vcc, s[0:1]
	v_add_u32_e32 v68, 21, v0
	v_cndmask_b32_e64 v78, v67, v210, s[0:1]
	v_cmp_gt_i32_e64 s[0:1], v68, v120
	v_add_f32_e32 v67, v79, v71
	s_and_b64 s[0:1], vcc, s[0:1]
	v_add_u32_e32 v68, 22, v0
	v_max3_f32 v66, v145, v74, v75
	v_cndmask_b32_e64 v145, v67, v210, s[0:1]
	v_cmp_gt_i32_e64 s[0:1], v68, v120
	v_add_f32_e32 v67, v80, v72
	s_and_b64 s[0:1], vcc, s[0:1]
	v_add_u32_e32 v68, 23, v0
	v_cndmask_b32_e64 v148, v67, v210, s[0:1]
	v_cmp_gt_i32_e64 s[0:1], v68, v120
	v_max3_f32 v66, v66, v76, v77
	v_add_f32_e32 v67, v81, v73
	s_and_b64 s[0:1], vcc, s[0:1]
	v_max3_f32 v66, v66, v78, v145
	v_cndmask_b32_e64 v81, v67, v210, s[0:1]
	v_max3_f32 v79, v66, v148, v81
	ds_read_b128 v[66:69], v134 offset:36992
	ds_read_b128 v[70:73], v134 offset:37008
	v_add_u32_e32 v80, 32, v0
	v_cmp_gt_i32_e64 s[0:1], v80, v120
	s_and_b64 s[0:1], vcc, s[0:1]
	s_waitcnt lgkmcnt(1)
	v_add_f32_e32 v50, v50, v66
	v_cndmask_b32_e64 v66, v50, v210, s[0:1]
	v_cmp_ge_i32_e64 s[0:1], v80, v120
	v_add_f32_e32 v50, v51, v67
	s_and_b64 s[0:1], vcc, s[0:1]
	v_add_f32_e32 v51, v52, v68
	v_add_u32_e32 v52, 34, v0
	v_cndmask_b32_e64 v67, v50, v210, s[0:1]
	v_cmp_gt_i32_e64 s[0:1], v52, v120
	s_and_b64 s[0:1], vcc, s[0:1]
	v_add_u32_e32 v52, 35, v0
	v_cndmask_b32_e64 v68, v51, v210, s[0:1]
	v_cmp_gt_i32_e64 s[0:1], v52, v120
	v_add_f32_e32 v51, v53, v69
	s_and_b64 s[0:1], vcc, s[0:1]
	v_add_u32_e32 v52, 36, v0
	v_cndmask_b32_e64 v69, v51, v210, s[0:1]
	v_cmp_gt_i32_e64 s[0:1], v52, v120
	s_waitcnt lgkmcnt(0)
	v_add_f32_e32 v51, v54, v70
	s_and_b64 s[0:1], vcc, s[0:1]
	v_add_u32_e32 v52, 37, v0
	v_cndmask_b32_e64 v70, v51, v210, s[0:1]
	v_cmp_gt_i32_e64 s[0:1], v52, v120
	v_add_f32_e32 v51, v55, v71
	s_and_b64 s[0:1], vcc, s[0:1]
	v_add_u32_e32 v52, 38, v0
	v_cndmask_b32_e64 v71, v51, v210, s[0:1]
	v_cmp_gt_i32_e64 s[0:1], v52, v120
	v_add_f32_e32 v51, v56, v72
	s_and_b64 s[0:1], vcc, s[0:1]
	v_add_u32_e32 v52, 39, v0
	v_max3_f32 v50, v79, v66, v67
	v_cndmask_b32_e64 v72, v51, v210, s[0:1]
	v_cmp_gt_i32_e64 s[0:1], v52, v120
	v_max3_f32 v50, v50, v68, v69
	v_add_f32_e32 v51, v57, v73
	s_and_b64 s[0:1], vcc, s[0:1]
	v_max3_f32 v50, v50, v70, v71
	v_cndmask_b32_e64 v73, v51, v210, s[0:1]
	v_max3_f32 v79, v50, v72, v73
	ds_read_b128 v[50:53], v134 offset:37056
	ds_read_b128 v[54:57], v134 offset:37072
	v_add_u32_e32 v80, 48, v0
	v_cmp_gt_i32_e64 s[0:1], v80, v120
	s_and_b64 s[0:1], vcc, s[0:1]
	s_waitcnt lgkmcnt(1)
	v_add_f32_e32 v50, v58, v50
	v_cndmask_b32_e64 v149, v50, v210, s[0:1]
	v_cmp_ge_i32_e64 s[0:1], v80, v120
	v_add_f32_e32 v50, v59, v51
	s_and_b64 s[0:1], vcc, s[0:1]
	v_add_f32_e32 v51, v60, v52
	v_add_u32_e32 v52, 50, v0
	v_cndmask_b32_e64 v59, v50, v210, s[0:1]
	v_cmp_gt_i32_e64 s[0:1], v52, v120
	s_and_b64 s[0:1], vcc, s[0:1]
	v_add_u32_e32 v52, 51, v0
	v_max3_f32 v50, v79, v149, v59
	v_cndmask_b32_e64 v79, v51, v210, s[0:1]
	v_cmp_gt_i32_e64 s[0:1], v52, v120
	v_add_f32_e32 v51, v61, v53
	s_and_b64 s[0:1], vcc, s[0:1]
	v_add_u32_e32 v52, 52, v0
	v_cndmask_b32_e64 v61, v51, v210, s[0:1]
	v_cmp_gt_i32_e64 s[0:1], v52, v120
	s_waitcnt lgkmcnt(0)
	v_add_f32_e32 v51, v62, v54
	s_and_b64 s[0:1], vcc, s[0:1]
	v_add_u32_e32 v52, 53, v0
	v_cndmask_b32_e64 v62, v51, v210, s[0:1]
	v_cmp_gt_i32_e64 s[0:1], v52, v120
	v_add_f32_e32 v51, v63, v55
	s_and_b64 s[0:1], vcc, s[0:1]
	v_add_u32_e32 v52, 54, v0
	v_cndmask_b32_e64 v55, v51, v210, s[0:1]
	v_cmp_gt_i32_e64 s[0:1], v52, v120
	v_add_f32_e32 v51, v64, v56
	s_and_b64 s[0:1], vcc, s[0:1]
	v_add_u32_e32 v0, 55, v0
	v_cndmask_b32_e64 v162, v51, v210, s[0:1]
	v_cmp_gt_i32_e64 s[0:1], v0, v120
	v_max3_f32 v50, v50, v79, v61
	v_add_f32_e32 v51, v65, v57
	s_and_b64 vcc, vcc, s[0:1]
	v_max3_f32 v50, v50, v62, v55
	v_cndmask_b32_e32 v163, v51, v210, vcc
	v_and_b32_e32 v51, 64, v207
	v_max3_f32 v0, v50, v162, v163
	v_xor_b32_e32 v50, 32, v207
	v_add_u32_e32 v51, 64, v51
	v_cmp_lt_i32_e32 vcc, v50, v51
	s_nop 1
	v_cndmask_b32_e32 v50, v207, v50, vcc
	v_lshlrev_b32_e32 v50, 2, v50
	ds_bpermute_b32 v50, v50, v0
	s_waitcnt lgkmcnt(0)
	v_max3_f32 v63, v136, v0, v50
	v_sub_f32_e32 v52, v139, v63
	v_exp_f32_e32 v167, v52
	v_sub_f32_e32 v52, v68, v63
	v_sub_f32_e32 v56, v141, v63
	v_sub_f32_e32 v0, v137, v63
	v_exp_f32_e32 v168, v52
	v_sub_f32_e32 v52, v140, v63
	v_exp_f32_e32 v140, v56
	v_sub_f32_e32 v56, v70, v63
	v_sub_f32_e32 v60, v143, v63
	v_exp_f32_e32 v165, v0
	v_sub_f32_e32 v0, v66, v63
	v_exp_f32_e32 v141, v56
	v_sub_f32_e32 v56, v142, v63
	v_exp_f32_e32 v142, v60
	v_sub_f32_e32 v60, v72, v63
	v_sub_f32_e32 v66, v74, v63
	v_exp_f32_e32 v143, v60
	v_sub_f32_e32 v60, v144, v63
	v_exp_f32_e32 v144, v66
	v_sub_f32_e32 v66, v149, v63
	v_exp_f32_e32 v149, v66
	v_sub_f32_e32 v66, v75, v63
	v_sub_f32_e32 v59, v59, v63
	v_exp_f32_e32 v68, v66
	v_exp_f32_e32 v66, v59
	v_sub_f32_e32 v59, v76, v63
	v_exp_f32_e32 v169, v59
	v_sub_f32_e32 v59, v79, v63
	v_exp_f32_e32 v166, v0
	v_sub_f32_e32 v0, v138, v63
	v_sub_f32_e32 v50, v67, v63
	v_exp_f32_e32 v170, v59
	v_sub_f32_e32 v59, v77, v63
	v_exp_f32_e32 v0, v0
	v_exp_f32_e32 v50, v50
	v_exp_f32_e32 v76, v59
	v_sub_f32_e32 v59, v61, v63
	v_exp_f32_e32 v74, v59
	v_sub_f32_e32 v59, v78, v63
	v_sub_f32_e32 v55, v55, v63
	v_exp_f32_e32 v54, v52
	v_sub_f32_e32 v52, v69, v63
	v_exp_f32_e32 v171, v59
	v_sub_f32_e32 v59, v62, v63
	v_exp_f32_e32 v78, v55
	v_sub_f32_e32 v55, v148, v63
	v_add_f32_e32 v51, v166, v165
	v_exp_f32_e32 v52, v52
	v_exp_f32_e32 v172, v59
	v_sub_f32_e32 v59, v145, v63
	v_exp_f32_e32 v145, v55
	v_sub_f32_e32 v55, v162, v63
	v_exp_f32_e32 v58, v56
	v_sub_f32_e32 v56, v71, v63
	v_exp_f32_e32 v148, v55
	v_sub_f32_e32 v55, v81, v63
	v_pk_add_f32 v[70:71], v[50:51], v[0:1]
	v_exp_f32_e32 v138, v55
	v_sub_f32_e32 v55, v163, v63
	v_pk_add_f32 v[70:71], v[70:71], v[70:71] op_sel_hi:[0,1]
	v_sub_f32_e32 v164, v136, v63
	v_add_f32_e32 v53, v168, v167
	v_exp_f32_e32 v56, v56
	v_exp_f32_e32 v136, v55
	v_mov_b32_e32 v55, v71
	v_pk_add_f32 v[70:71], v[52:53], v[54:55]
	v_sub_f32_e32 v64, v73, v63
	v_pk_add_f32 v[70:71], v[70:71], v[70:71] op_sel_hi:[0,1]
	v_add_f32_e32 v57, v141, v140
	v_exp_f32_e32 v60, v60
	v_exp_f32_e32 v64, v64
	v_exp_f32_e32 v80, v59
	v_mov_b32_e32 v59, v71
	v_pk_add_f32 v[70:71], v[56:57], v[58:59]
	v_add_f32_e32 v65, v143, v142
	v_pk_add_f32 v[70:71], v[70:71], v[70:71] op_sel_hi:[0,1]
	v_mov_b32_e32 v61, v71
	v_pk_add_f32 v[70:71], v[64:65], v[60:61]
	v_add_f32_e32 v67, v149, v144
	v_pk_add_f32 v[70:71], v[70:71], v[70:71] op_sel_hi:[0,1]
	v_mov_b32_e32 v69, v71
	v_pk_add_f32 v[70:71], v[66:67], v[68:69]
	v_add_f32_e32 v75, v170, v169
	v_pk_add_f32 v[70:71], v[70:71], v[70:71] op_sel_hi:[0,1]
	v_mov_b32_e32 v77, v71
	v_pk_add_f32 v[70:71], v[74:75], v[76:77]
	v_add_f32_e32 v79, v172, v171
	v_pk_add_f32 v[70:71], v[70:71], v[70:71] op_sel_hi:[0,1]
	v_mov_b32_e32 v81, v71
	v_pk_add_f32 v[70:71], v[78:79], v[80:81]
	v_add_f32_e32 v137, v148, v145
	v_pk_add_f32 v[70:71], v[70:71], v[70:71] op_sel_hi:[0,1]
	v_mov_b32_e32 v139, v71
	v_exp_f32_e32 v62, v164
	v_pk_add_f32 v[70:71], v[136:137], v[138:139]
	v_cvt_pk_bf16_f32 v72, v140, v58
	v_add_f32_e32 v65, v70, v71
	v_cvt_pk_bf16_f32 v70, v165, v0
	v_add_u32_e32 v0, v132, v122
	v_cvt_pk_bf16_f32 v71, v167, v54
	v_cvt_pk_bf16_f32 v73, v142, v60
	v_cvt_pk_bf16_f32 v58, v144, v68
	v_cvt_pk_bf16_f32 v59, v169, v76
	v_cvt_pk_bf16_f32 v60, v171, v80
	v_cvt_pk_bf16_f32 v54, v166, v50
	v_cvt_pk_bf16_f32 v55, v168, v52
	v_cvt_pk_bf16_f32 v50, v149, v66
	v_cvt_pk_bf16_f32 v51, v170, v74
	v_cvt_pk_bf16_f32 v52, v172, v78
	ds_read_b128 v[66:69], v0 offset:23040
	ds_read_b128 v[74:77], v0 offset:18432
	ds_read_b128 v[78:81], v0 offset:18464
	v_pk_mul_f32 v[16:17], v[16:17], v[62:63] op_sel_hi:[1,0]
	v_pk_mul_f32 v[14:15], v[14:15], v[62:63] op_sel_hi:[1,0]
	v_pk_mul_f32 v[12:13], v[12:13], v[62:63] op_sel_hi:[1,0]
	v_pk_mul_f32 v[10:11], v[10:11], v[62:63] op_sel_hi:[1,0]
	v_pk_mul_f32 v[8:9], v[8:9], v[62:63] op_sel_hi:[1,0]
	v_pk_mul_f32 v[6:7], v[6:7], v[62:63] op_sel_hi:[1,0]
	v_pk_mul_f32 v[4:5], v[4:5], v[62:63] op_sel_hi:[1,0]
	v_pk_mul_f32 v[2:3], v[2:3], v[62:63] op_sel_hi:[1,0]
	v_pk_mul_f32 v[32:33], v[32:33], v[62:63] op_sel_hi:[1,0]
	v_pk_mul_f32 v[30:31], v[30:31], v[62:63] op_sel_hi:[1,0]
	v_pk_mul_f32 v[28:29], v[28:29], v[62:63] op_sel_hi:[1,0]
	v_pk_mul_f32 v[26:27], v[26:27], v[62:63] op_sel_hi:[1,0]
	v_pk_mul_f32 v[24:25], v[24:25], v[62:63] op_sel_hi:[1,0]
	v_pk_mul_f32 v[22:23], v[22:23], v[62:63] op_sel_hi:[1,0]
	v_pk_mul_f32 v[20:21], v[20:21], v[62:63] op_sel_hi:[1,0]
	v_pk_mul_f32 v[18:19], v[18:19], v[62:63] op_sel_hi:[1,0]
	s_waitcnt lgkmcnt(2)
	v_mfma_f32_32x32x16_bf16 v[2:17], v[66:69], v[70:73], v[2:17]
	ds_read_b128 v[66:69], v0 offset:23072
	v_cvt_pk_bf16_f32 v61, v145, v138
	v_cvt_pk_bf16_f32 v56, v141, v56
	v_cvt_pk_bf16_f32 v57, v143, v64
	v_cvt_pk_bf16_f32 v53, v148, v136
	v_fmac_f32_e32 v65, v133, v62
	v_mov_b32_e32 v133, v65
	s_waitcnt lgkmcnt(2)
	v_mfma_f32_32x32x16_bf16 v[18:33], v[74:77], v[70:73], v[18:33]
	v_mov_b32_e32 v136, v63
	s_waitcnt lgkmcnt(1)
	v_mfma_f32_32x32x16_bf16 v[18:33], v[78:81], v[58:61], v[18:33]
	s_waitcnt lgkmcnt(0)
	v_mfma_f32_32x32x16_bf16 v[2:17], v[66:69], v[58:61], v[2:17]
	ds_read_b128 v[58:61], v0 offset:18496
	ds_read_b128 v[66:69], v0 offset:23104
	s_waitcnt lgkmcnt(1)
	v_mfma_f32_32x32x16_bf16 v[18:33], v[58:61], v[54:57], v[18:33]
	s_waitcnt lgkmcnt(0)
	v_mfma_f32_32x32x16_bf16 v[2:17], v[66:69], v[54:57], v[2:17]
	ds_read_b128 v[54:57], v0 offset:18528
	ds_read_b128 v[58:61], v0 offset:23136
	s_waitcnt lgkmcnt(1)
	v_mfma_f32_32x32x16_bf16 v[18:33], v[54:57], v[50:53], v[18:33]
	s_waitcnt lgkmcnt(0)
	v_mfma_f32_32x32x16_bf16 v[2:17], v[58:61], v[50:53], v[2:17]
.Lattn_join_A:
	s_or_b64 exec, exec, s[12:13]
	s_cmp_ge_i32 s7, s40
	s_cbranch_scc0 .LBB0_394

.Lattn_fast_B:
	s_waitcnt lgkmcnt(1)
	v_mfma_f32_32x32x16_bf16 v[66:81], v[138:141], v[94:97], v[66:81]
	s_waitcnt lgkmcnt(0)
	v_mfma_f32_32x32x16_bf16 v[50:65], v[142:145], v[94:97], v[50:65]
	ds_read_b128 v[138:141], v134 offset:37120
	ds_read_b128 v[142:145], v134 offset:37136
	s_waitcnt lgkmcnt(1)
	s_nop 6
	v_add_f32_e32 v138, v66, v138
	v_add_f32_e32 v137, v67, v139
	s_mov_b32 s0, 0xf149f2ca
	v_add_f32_e32 v139, v68, v140
	v_max3_f32 v66, v138, s0, v137
	v_add_f32_e32 v140, v69, v141
	s_waitcnt lgkmcnt(0)
	v_add_f32_e32 v141, v70, v142
	v_add_f32_e32 v142, v71, v143
	v_add_f32_e32 v143, v72, v144
	v_max3_f32 v66, v66, v139, v140
	v_add_f32_e32 v144, v73, v145
	v_max3_f32 v66, v66, v141, v142
	v_max3_f32 v145, v66, v143, v144
	ds_read_b128 v[66:69], v134 offset:37184
	ds_read_b128 v[70:73], v134 offset:37200
	s_waitcnt lgkmcnt(1)
	v_add_f32_e32 v74, v74, v66
	v_add_f32_e32 v75, v75, v67
	v_add_f32_e32 v76, v76, v68
	v_add_f32_e32 v77, v77, v69
	s_waitcnt lgkmcnt(0)
	v_add_f32_e32 v78, v78, v70
	v_add_f32_e32 v67, v79, v71
	v_max3_f32 v66, v145, v74, v75
	v_mov_b32_e32 v145, v67
	v_add_f32_e32 v148, v80, v72
	v_max3_f32 v66, v66, v76, v77
	v_add_f32_e32 v81, v81, v73
	v_max3_f32 v66, v66, v78, v145
	v_max3_f32 v79, v66, v148, v81
	ds_read_b128 v[66:69], v134 offset:37248
	ds_read_b128 v[70:73], v134 offset:37264
	s_waitcnt lgkmcnt(1)
	v_add_f32_e32 v66, v50, v66
	v_add_f32_e32 v67, v51, v67
	v_add_f32_e32 v68, v52, v68
	v_add_f32_e32 v69, v53, v69
	s_waitcnt lgkmcnt(0)
	v_add_f32_e32 v70, v54, v70
	v_add_f32_e32 v71, v55, v71
	v_add_f32_e32 v72, v56, v72
	v_max3_f32 v50, v79, v66, v67
	v_max3_f32 v50, v50, v68, v69
	v_add_f32_e32 v73, v57, v73
	v_max3_f32 v50, v50, v70, v71
	v_max3_f32 v79, v50, v72, v73
	ds_read_b128 v[50:53], v134 offset:37312
	ds_read_b128 v[54:57], v134 offset:37328
	s_waitcnt lgkmcnt(1)
	v_add_f32_e32 v149, v58, v50
	v_add_f32_e32 v80, v59, v51
	v_add_f32_e32 v51, v60, v52
	v_max3_f32 v50, v79, v149, v80
	v_mov_b32_e32 v79, v51
	v_add_f32_e32 v53, v61, v53
	s_waitcnt lgkmcnt(0)
	v_add_f32_e32 v62, v62, v54
	v_add_f32_e32 v162, v63, v55
	v_add_f32_e32 v163, v64, v56
	v_add_u32_e32 v0, 0x77, v0
	v_max3_f32 v50, v50, v79, v53
	v_add_f32_e32 v57, v65, v57
	v_max3_f32 v50, v50, v62, v162
	v_and_b32_e32 v51, 64, v207
	v_max3_f32 v0, v50, v163, v57
	v_xor_b32_e32 v50, 32, v207
	v_add_u32_e32 v51, 64, v51
	v_cmp_lt_i32_e32 vcc, v50, v51
	s_nop 1
	v_cndmask_b32_e32 v50, v207, v50, vcc
	v_lshlrev_b32_e32 v50, 2, v50
	ds_bpermute_b32 v50, v50, v0
	s_waitcnt lgkmcnt(0)
	v_max3_f32 v63, v136, v0, v50
	v_sub_f32_e32 v0, v138, v63
	v_exp_f32_e32 v164, v0
	v_sub_f32_e32 v0, v66, v63
	v_sub_f32_e32 v52, v139, v63
	v_exp_f32_e32 v165, v0
	v_sub_f32_e32 v0, v137, v63
	v_exp_f32_e32 v166, v52
	v_sub_f32_e32 v52, v68, v63
	v_sub_f32_e32 v56, v141, v63
	v_sub_f32_e32 v53, v53, v63
	v_exp_f32_e32 v50, v0
	v_sub_f32_e32 v0, v67, v63
	v_exp_f32_e32 v167, v52
	v_sub_f32_e32 v52, v140, v63
	v_exp_f32_e32 v140, v56
	v_sub_f32_e32 v56, v70, v63
	v_sub_f32_e32 v60, v143, v63
	v_sub_f32_e32 v67, v76, v63
	v_exp_f32_e32 v76, v53
	v_sub_f32_e32 v53, v78, v63
	v_exp_f32_e32 v141, v56
	v_sub_f32_e32 v56, v142, v63
	v_exp_f32_e32 v142, v60
	v_sub_f32_e32 v60, v72, v63
	v_sub_f32_e32 v66, v74, v63
	v_exp_f32_e32 v170, v53
	v_sub_f32_e32 v53, v62, v63
	v_exp_f32_e32 v0, v0
	v_exp_f32_e32 v143, v60
	v_sub_f32_e32 v60, v144, v63
	v_exp_f32_e32 v144, v66
	v_sub_f32_e32 v66, v149, v63
	v_exp_f32_e32 v171, v53
	v_sub_f32_e32 v53, v145, v63
	v_exp_f32_e32 v149, v66
	v_sub_f32_e32 v66, v75, v63
	v_exp_f32_e32 v78, v53
	v_sub_f32_e32 v53, v162, v63
	v_exp_f32_e32 v54, v52
	v_sub_f32_e32 v52, v69, v63
	v_exp_f32_e32 v68, v66
	v_sub_f32_e32 v66, v80, v63
	v_exp_f32_e32 v80, v53
	v_sub_f32_e32 v53, v148, v63
	v_add_f32_e32 v51, v164, v165
	v_exp_f32_e32 v52, v52
	v_exp_f32_e32 v145, v53
	v_sub_f32_e32 v53, v163, v63
	v_exp_f32_e32 v58, v56
	v_sub_f32_e32 v56, v71, v63
	v_exp_f32_e32 v148, v53
	v_sub_f32_e32 v53, v81, v63
	v_pk_add_f32 v[70:71], v[50:51], v[0:1]
	v_sub_f32_e32 v65, v136, v63
	v_exp_f32_e32 v136, v53
	v_sub_f32_e32 v53, v57, v63
	v_pk_add_f32 v[70:71], v[70:71], v[70:71] op_sel_hi:[0,1]
	v_add_f32_e32 v55, v166, v167
	v_exp_f32_e32 v56, v56
	v_exp_f32_e32 v138, v53
	v_mov_b32_e32 v53, v71
	v_pk_add_f32 v[70:71], v[54:55], v[52:53]
	v_sub_f32_e32 v64, v73, v63
	v_pk_add_f32 v[70:71], v[70:71], v[70:71] op_sel_hi:[0,1]
	v_add_f32_e32 v59, v140, v141
	v_exp_f32_e32 v60, v60
	v_exp_f32_e32 v64, v64
	v_mov_b32_e32 v57, v71
	v_pk_add_f32 v[70:71], v[58:59], v[56:57]
	v_add_f32_e32 v61, v142, v143
	v_pk_add_f32 v[70:71], v[70:71], v[70:71] op_sel_hi:[0,1]
	v_exp_f32_e32 v66, v66
	v_exp_f32_e32 v62, v65
	v_mov_b32_e32 v65, v71
	v_exp_f32_e32 v168, v67
	v_sub_f32_e32 v67, v79, v63
	v_pk_add_f32 v[70:71], v[60:61], v[64:65]
	v_exp_f32_e32 v169, v67
	v_sub_f32_e32 v67, v77, v63
	v_pk_add_f32 v[70:71], v[70:71], v[70:71] op_sel_hi:[0,1]
	v_add_f32_e32 v69, v144, v149
	v_exp_f32_e32 v74, v67
	v_mov_b32_e32 v67, v71
	v_pk_add_f32 v[70:71], v[68:69], v[66:67]
	v_add_f32_e32 v75, v168, v169
	v_pk_add_f32 v[70:71], v[70:71], v[70:71] op_sel_hi:[0,1]
	v_mov_b32_e32 v77, v71
	v_pk_add_f32 v[70:71], v[74:75], v[76:77]
	v_add_f32_e32 v79, v170, v171
	v_pk_add_f32 v[70:71], v[70:71], v[70:71] op_sel_hi:[0,1]
	v_mov_b32_e32 v81, v71
	v_pk_add_f32 v[70:71], v[78:79], v[80:81]
	v_add_f32_e32 v137, v145, v148
	v_pk_add_f32 v[70:71], v[70:71], v[70:71] op_sel_hi:[0,1]
	v_mov_b32_e32 v139, v71
	v_pk_add_f32 v[70:71], v[136:137], v[138:139]
	v_cvt_pk_bf16_f32 v72, v140, v58
	v_add_f32_e32 v65, v70, v71
	v_cvt_pk_bf16_f32 v71, v166, v54
	v_cvt_pk_bf16_f32 v54, v165, v0
	v_add_u32_e32 v0, v132, v122
	v_cvt_pk_bf16_f32 v70, v164, v50
	v_cvt_pk_bf16_f32 v73, v142, v60
	v_cvt_pk_bf16_f32 v58, v144, v68
	v_cvt_pk_bf16_f32 v59, v168, v74
	v_cvt_pk_bf16_f32 v60, v170, v78
	v_cvt_pk_bf16_f32 v55, v167, v52
	v_cvt_pk_bf16_f32 v50, v149, v66
	v_cvt_pk_bf16_f32 v51, v169, v76
	v_cvt_pk_bf16_f32 v52, v171, v80
	ds_read_b128 v[66:69], v0 offset:32256
	ds_read_b128 v[74:77], v0 offset:27648
	ds_read_b128 v[78:81], v0 offset:27680
	v_pk_mul_f32 v[16:17], v[16:17], v[62:63] op_sel_hi:[1,0]
	v_pk_mul_f32 v[14:15], v[14:15], v[62:63] op_sel_hi:[1,0]
	v_pk_mul_f32 v[12:13], v[12:13], v[62:63] op_sel_hi:[1,0]
	v_pk_mul_f32 v[10:11], v[10:11], v[62:63] op_sel_hi:[1,0]
	v_pk_mul_f32 v[8:9], v[8:9], v[62:63] op_sel_hi:[1,0]
	v_pk_mul_f32 v[6:7], v[6:7], v[62:63] op_sel_hi:[1,0]
	v_pk_mul_f32 v[4:5], v[4:5], v[62:63] op_sel_hi:[1,0]
	v_pk_mul_f32 v[2:3], v[2:3], v[62:63] op_sel_hi:[1,0]
	v_pk_mul_f32 v[32:33], v[32:33], v[62:63] op_sel_hi:[1,0]
	v_pk_mul_f32 v[30:31], v[30:31], v[62:63] op_sel_hi:[1,0]
	v_pk_mul_f32 v[28:29], v[28:29], v[62:63] op_sel_hi:[1,0]
	v_pk_mul_f32 v[26:27], v[26:27], v[62:63] op_sel_hi:[1,0]
	v_pk_mul_f32 v[24:25], v[24:25], v[62:63] op_sel_hi:[1,0]
	v_pk_mul_f32 v[22:23], v[22:23], v[62:63] op_sel_hi:[1,0]
	v_pk_mul_f32 v[20:21], v[20:21], v[62:63] op_sel_hi:[1,0]
	v_pk_mul_f32 v[18:19], v[18:19], v[62:63] op_sel_hi:[1,0]
	s_waitcnt lgkmcnt(2)
	v_mfma_f32_32x32x16_bf16 v[2:17], v[66:69], v[70:73], v[2:17]
	ds_read_b128 v[66:69], v0 offset:32288
	v_cvt_pk_bf16_f32 v61, v145, v136
	v_cvt_pk_bf16_f32 v56, v141, v56
	v_cvt_pk_bf16_f32 v57, v143, v64
	v_cvt_pk_bf16_f32 v53, v148, v138
	v_fmac_f32_e32 v65, v133, v62
	v_mov_b32_e32 v136, v63
	s_waitcnt lgkmcnt(2)
	v_mfma_f32_32x32x16_bf16 v[18:33], v[74:77], v[70:73], v[18:33]
	v_mov_b32_e32 v133, v65
	s_waitcnt lgkmcnt(1)
	v_mfma_f32_32x32x16_bf16 v[18:33], v[78:81], v[58:61], v[18:33]
	s_waitcnt lgkmcnt(0)
	v_mfma_f32_32x32x16_bf16 v[2:17], v[66:69], v[58:61], v[2:17]
	ds_read_b128 v[58:61], v0 offset:27712
	ds_read_b128 v[66:69], v0 offset:32320
	s_waitcnt lgkmcnt(1)
	v_mfma_f32_32x32x16_bf16 v[18:33], v[58:61], v[54:57], v[18:33]
	s_waitcnt lgkmcnt(0)
	v_mfma_f32_32x32x16_bf16 v[2:17], v[66:69], v[54:57], v[2:17]
	ds_read_b128 v[54:57], v0 offset:27744
	ds_read_b128 v[58:61], v0 offset:32352
	s_waitcnt lgkmcnt(1)
	v_mfma_f32_32x32x16_bf16 v[18:33], v[54:57], v[50:53], v[18:33]
	s_waitcnt lgkmcnt(0)
	v_mfma_f32_32x32x16_bf16 v[2:17], v[58:61], v[50:53], v[2:17]
	s_branch .LBB0_402
.Lattn_fast_A:
	s_waitcnt lgkmcnt(1)
	v_mfma_f32_32x32x16_bf16 v[66:81], v[138:141], v[94:97], v[66:81]
	s_waitcnt lgkmcnt(0)
	v_mfma_f32_32x32x16_bf16 v[50:65], v[142:145], v[94:97], v[50:65]
	ds_read_b128 v[138:141], v134 offset:36864
	ds_read_b128 v[142:145], v134 offset:36880
	s_waitcnt lgkmcnt(1)
	s_nop 6
	v_add_f32_e32 v137, v66, v138
	v_add_f32_e32 v138, v67, v139
	s_mov_b32 s0, 0xf149f2ca
	v_add_f32_e32 v139, v68, v140
	v_max3_f32 v66, v137, s0, v138
	v_add_f32_e32 v140, v69, v141
	s_waitcnt lgkmcnt(0)
	v_add_f32_e32 v141, v70, v142
	v_add_f32_e32 v142, v71, v143
	v_add_f32_e32 v143, v72, v144
	v_max3_f32 v66, v66, v139, v140
	v_add_f32_e32 v144, v73, v145
	v_max3_f32 v66, v66, v141, v142
	v_max3_f32 v145, v66, v143, v144
	ds_read_b128 v[66:69], v134 offset:36928
	ds_read_b128 v[70:73], v134 offset:36944
	s_waitcnt lgkmcnt(1)
	v_add_f32_e32 v74, v74, v66
	v_add_f32_e32 v75, v75, v67
	v_add_f32_e32 v76, v76, v68
	v_add_f32_e32 v77, v77, v69
	s_waitcnt lgkmcnt(0)
	v_add_f32_e32 v78, v78, v70
	v_add_f32_e32 v67, v79, v71
	v_max3_f32 v66, v145, v74, v75
	v_mov_b32_e32 v145, v67
	v_add_f32_e32 v148, v80, v72
	v_max3_f32 v66, v66, v76, v77
	v_add_f32_e32 v81, v81, v73
	v_max3_f32 v66, v66, v78, v145
	v_max3_f32 v79, v66, v148, v81
	ds_read_b128 v[66:69], v134 offset:36992
	ds_read_b128 v[70:73], v134 offset:37008
	s_waitcnt lgkmcnt(1)
	v_add_f32_e32 v66, v50, v66
	v_add_f32_e32 v67, v51, v67
	v_add_f32_e32 v68, v52, v68
	v_add_f32_e32 v69, v53, v69
	s_waitcnt lgkmcnt(0)
	v_add_f32_e32 v70, v54, v70
	v_add_f32_e32 v71, v55, v71
	v_add_f32_e32 v72, v56, v72
	v_max3_f32 v50, v79, v66, v67
	v_max3_f32 v50, v50, v68, v69
	v_add_f32_e32 v73, v57, v73
	v_max3_f32 v50, v50, v70, v71
	v_max3_f32 v79, v50, v72, v73
	ds_read_b128 v[50:53], v134 offset:37056
	ds_read_b128 v[54:57], v134 offset:37072
	s_waitcnt lgkmcnt(1)
	v_add_f32_e32 v149, v58, v50
	v_add_f32_e32 v59, v59, v51
	v_add_f32_e32 v51, v60, v52
	v_max3_f32 v50, v79, v149, v59
	v_mov_b32_e32 v79, v51
	v_add_f32_e32 v61, v61, v53
	s_waitcnt lgkmcnt(0)
	v_add_f32_e32 v62, v62, v54
	v_add_f32_e32 v55, v63, v55
	v_add_f32_e32 v162, v64, v56
	v_add_u32_e32 v0, 55, v0
	v_max3_f32 v50, v50, v79, v61
	v_add_f32_e32 v163, v65, v57
	v_max3_f32 v50, v50, v62, v55
	v_and_b32_e32 v51, 64, v207
	v_max3_f32 v0, v50, v162, v163
	v_xor_b32_e32 v50, 32, v207
	v_add_u32_e32 v51, 64, v51
	v_cmp_lt_i32_e32 vcc, v50, v51
	s_nop 1
	v_cndmask_b32_e32 v50, v207, v50, vcc
	v_lshlrev_b32_e32 v50, 2, v50
	ds_bpermute_b32 v50, v50, v0
	s_waitcnt lgkmcnt(0)
	v_max3_f32 v63, v136, v0, v50
	v_sub_f32_e32 v52, v139, v63
	v_exp_f32_e32 v167, v52
	v_sub_f32_e32 v52, v68, v63
	v_sub_f32_e32 v56, v141, v63
	v_sub_f32_e32 v0, v137, v63
	v_exp_f32_e32 v168, v52
	v_sub_f32_e32 v52, v140, v63
	v_exp_f32_e32 v140, v56
	v_sub_f32_e32 v56, v70, v63
	v_sub_f32_e32 v60, v143, v63
	v_exp_f32_e32 v165, v0
	v_sub_f32_e32 v0, v66, v63
	v_exp_f32_e32 v141, v56
	v_sub_f32_e32 v56, v142, v63
	v_exp_f32_e32 v142, v60
	v_sub_f32_e32 v60, v72, v63
	v_sub_f32_e32 v66, v74, v63
	v_exp_f32_e32 v143, v60
	v_sub_f32_e32 v60, v144, v63
	v_exp_f32_e32 v144, v66
	v_sub_f32_e32 v66, v149, v63
	v_exp_f32_e32 v149, v66
	v_sub_f32_e32 v66, v75, v63
	v_sub_f32_e32 v59, v59, v63
	v_exp_f32_e32 v68, v66
	v_exp_f32_e32 v66, v59
	v_sub_f32_e32 v59, v76, v63
	v_exp_f32_e32 v169, v59
	v_sub_f32_e32 v59, v79, v63
	v_exp_f32_e32 v166, v0
	v_sub_f32_e32 v0, v138, v63
	v_sub_f32_e32 v50, v67, v63
	v_exp_f32_e32 v170, v59
	v_sub_f32_e32 v59, v77, v63
	v_exp_f32_e32 v0, v0
	v_exp_f32_e32 v50, v50
	v_exp_f32_e32 v76, v59
	v_sub_f32_e32 v59, v61, v63
	v_exp_f32_e32 v74, v59
	v_sub_f32_e32 v59, v78, v63
	v_sub_f32_e32 v55, v55, v63
	v_exp_f32_e32 v54, v52
	v_sub_f32_e32 v52, v69, v63
	v_exp_f32_e32 v171, v59
	v_sub_f32_e32 v59, v62, v63
	v_exp_f32_e32 v78, v55
	v_sub_f32_e32 v55, v148, v63
	v_add_f32_e32 v51, v166, v165
	v_exp_f32_e32 v52, v52
	v_exp_f32_e32 v172, v59
	v_sub_f32_e32 v59, v145, v63
	v_exp_f32_e32 v145, v55
	v_sub_f32_e32 v55, v162, v63
	v_exp_f32_e32 v58, v56
	v_sub_f32_e32 v56, v71, v63
	v_exp_f32_e32 v148, v55
	v_sub_f32_e32 v55, v81, v63
	v_pk_add_f32 v[70:71], v[50:51], v[0:1]
	v_exp_f32_e32 v138, v55
	v_sub_f32_e32 v55, v163, v63
	v_pk_add_f32 v[70:71], v[70:71], v[70:71] op_sel_hi:[0,1]
	v_sub_f32_e32 v164, v136, v63
	v_add_f32_e32 v53, v168, v167
	v_exp_f32_e32 v56, v56
	v_exp_f32_e32 v136, v55
	v_mov_b32_e32 v55, v71
	v_pk_add_f32 v[70:71], v[52:53], v[54:55]
	v_sub_f32_e32 v64, v73, v63
	v_pk_add_f32 v[70:71], v[70:71], v[70:71] op_sel_hi:[0,1]
	v_add_f32_e32 v57, v141, v140
	v_exp_f32_e32 v60, v60
	v_exp_f32_e32 v64, v64
	v_exp_f32_e32 v80, v59
	v_mov_b32_e32 v59, v71
	v_pk_add_f32 v[70:71], v[56:57], v[58:59]
	v_add_f32_e32 v65, v143, v142
	v_pk_add_f32 v[70:71], v[70:71], v[70:71] op_sel_hi:[0,1]
	v_mov_b32_e32 v61, v71
	v_pk_add_f32 v[70:71], v[64:65], v[60:61]
	v_add_f32_e32 v67, v149, v144
	v_pk_add_f32 v[70:71], v[70:71], v[70:71] op_sel_hi:[0,1]
	v_mov_b32_e32 v69, v71
	v_pk_add_f32 v[70:71], v[66:67], v[68:69]
	v_add_f32_e32 v75, v170, v169
	v_pk_add_f32 v[70:71], v[70:71], v[70:71] op_sel_hi:[0,1]
	v_mov_b32_e32 v77, v71
	v_pk_add_f32 v[70:71], v[74:75], v[76:77]
	v_add_f32_e32 v79, v172, v171
	v_pk_add_f32 v[70:71], v[70:71], v[70:71] op_sel_hi:[0,1]
	v_mov_b32_e32 v81, v71
	v_pk_add_f32 v[70:71], v[78:79], v[80:81]
	v_add_f32_e32 v137, v148, v145
	v_pk_add_f32 v[70:71], v[70:71], v[70:71] op_sel_hi:[0,1]
	v_mov_b32_e32 v139, v71
	v_exp_f32_e32 v62, v164
	v_pk_add_f32 v[70:71], v[136:137], v[138:139]
	v_cvt_pk_bf16_f32 v72, v140, v58
	v_add_f32_e32 v65, v70, v71
	v_cvt_pk_bf16_f32 v70, v165, v0
	v_add_u32_e32 v0, v132, v122
	v_cvt_pk_bf16_f32 v71, v167, v54
	v_cvt_pk_bf16_f32 v73, v142, v60
	v_cvt_pk_bf16_f32 v58, v144, v68
	v_cvt_pk_bf16_f32 v59, v169, v76
	v_cvt_pk_bf16_f32 v60, v171, v80
	v_cvt_pk_bf16_f32 v54, v166, v50
	v_cvt_pk_bf16_f32 v55, v168, v52
	v_cvt_pk_bf16_f32 v50, v149, v66
	v_cvt_pk_bf16_f32 v51, v170, v74
	v_cvt_pk_bf16_f32 v52, v172, v78
	ds_read_b128 v[66:69], v0 offset:23040
	ds_read_b128 v[74:77], v0 offset:18432
	ds_read_b128 v[78:81], v0 offset:18464
	v_pk_mul_f32 v[16:17], v[16:17], v[62:63] op_sel_hi:[1,0]
	v_pk_mul_f32 v[14:15], v[14:15], v[62:63] op_sel_hi:[1,0]
	v_pk_mul_f32 v[12:13], v[12:13], v[62:63] op_sel_hi:[1,0]
	v_pk_mul_f32 v[10:11], v[10:11], v[62:63] op_sel_hi:[1,0]
	v_pk_mul_f32 v[8:9], v[8:9], v[62:63] op_sel_hi:[1,0]
	v_pk_mul_f32 v[6:7], v[6:7], v[62:63] op_sel_hi:[1,0]
	v_pk_mul_f32 v[4:5], v[4:5], v[62:63] op_sel_hi:[1,0]
	v_pk_mul_f32 v[2:3], v[2:3], v[62:63] op_sel_hi:[1,0]
	v_pk_mul_f32 v[32:33], v[32:33], v[62:63] op_sel_hi:[1,0]
	v_pk_mul_f32 v[30:31], v[30:31], v[62:63] op_sel_hi:[1,0]
	v_pk_mul_f32 v[28:29], v[28:29], v[62:63] op_sel_hi:[1,0]
	v_pk_mul_f32 v[26:27], v[26:27], v[62:63] op_sel_hi:[1,0]
	v_pk_mul_f32 v[24:25], v[24:25], v[62:63] op_sel_hi:[1,0]
	v_pk_mul_f32 v[22:23], v[22:23], v[62:63] op_sel_hi:[1,0]
	v_pk_mul_f32 v[20:21], v[20:21], v[62:63] op_sel_hi:[1,0]
	v_pk_mul_f32 v[18:19], v[18:19], v[62:63] op_sel_hi:[1,0]
	s_waitcnt lgkmcnt(2)
	v_mfma_f32_32x32x16_bf16 v[2:17], v[66:69], v[70:73], v[2:17]
	ds_read_b128 v[66:69], v0 offset:23072
	v_cvt_pk_bf16_f32 v61, v145, v138
	v_cvt_pk_bf16_f32 v56, v141, v56
	v_cvt_pk_bf16_f32 v57, v143, v64
	v_cvt_pk_bf16_f32 v53, v148, v136
	v_fmac_f32_e32 v65, v133, v62
	v_mov_b32_e32 v133, v65
	s_waitcnt lgkmcnt(2)
	v_mfma_f32_32x32x16_bf16 v[18:33], v[74:77], v[70:73], v[18:33]
	v_mov_b32_e32 v136, v63
	s_waitcnt lgkmcnt(1)
	v_mfma_f32_32x32x16_bf16 v[18:33], v[78:81], v[58:61], v[18:33]
	s_waitcnt lgkmcnt(0)
	v_mfma_f32_32x32x16_bf16 v[2:17], v[66:69], v[58:61], v[2:17]
	ds_read_b128 v[58:61], v0 offset:18496
	ds_read_b128 v[66:69], v0 offset:23104
	s_waitcnt lgkmcnt(1)
	v_mfma_f32_32x32x16_bf16 v[18:33], v[58:61], v[54:57], v[18:33]
	s_waitcnt lgkmcnt(0)
	v_mfma_f32_32x32x16_bf16 v[2:17], v[66:69], v[54:57], v[2:17]
	ds_read_b128 v[54:57], v0 offset:18528
	ds_read_b128 v[58:61], v0 offset:23136
	s_waitcnt lgkmcnt(1)
	v_mfma_f32_32x32x16_bf16 v[18:33], v[54:57], v[50:53], v[18:33]
	s_waitcnt lgkmcnt(0)
	v_mfma_f32_32x32x16_bf16 v[2:17], v[58:61], v[50:53], v[2:17]
	s_branch .Lattn_join_A
